# v39 = v37 + static s_setprio 1 for workgroups >= 256 (second workgroup per CU) inside the eight GEMM phases only
# baseline (speedup 1.0000x reference)
.LBB0_291:
	s_or_b64 exec, exec, s[0:1]
	s_waitcnt lgkmcnt(0)
	s_barrier
	s_cmpk_lt_u32 s96, 0x100
	s_cbranch_scc1 .Lprio_skip_7
	s_setprio 1
.Lprio_skip_7:
.LBB0_292:
	s_and_b32 s19, s96, 3
	s_mul_i32 s19, s19, 5
	v_sub_u32_e64 v0, s19, 14 clamp
	s_lshr_b32 s18, s96, 3
	v_readfirstlane_b32 s0, v0
	s_xor_b32 s20, s0, 5
	v_cvt_f32_ubyte0_e32 v0, s20
	v_rcp_iflag_f32_e32 v0, v0
	s_mul_i32 s22, s20, 0x48
	s_cmp_lt_u32 s18, s22
	s_cselect_b64 s[0:1], -1, 0
	v_mul_f32_e32 v0, 0x4f7ffffe, v0
	v_cvt_u32_f32_e32 v0, v0
	s_bfe_i32 s2, s96, 0x10002
	s_and_b32 s23, s2, 0x48
	s_lshr_b32 s2, s94, 1
	s_cmp_ge_u32 s96, s2
	s_cselect_b64 s[2:3], -1, 0
	s_sub_i32 s4, 0, s20
	v_readfirstlane_b32 s5, v0
	s_mul_i32 s4, s4, s5
	v_cndmask_b32_e64 v0, 0, 1, s[2:3]
	s_mul_hi_u32 s4, s5, s4
	v_cmp_ne_u32_e64 s[2:3], 1, v0
	v_cndmask_b32_e64 v0, 0, 1, s[0:1]
	s_movk_i32 s21, 0x48
	s_lshr_b32 s24, s94, 3
	s_mov_b32 s9, 0
	s_add_i32 s25, s5, s4
	v_cmp_ne_u32_e64 s[4:5], 1, v0
	v_mov_b32_e32 v177, 0
	s_mov_b32 s26, 0x10000
	s_mov_b32 s27, 0x20000
	s_mov_b32 s34, 0x30000
	s_mov_b32 s35, 0x40000
	s_mov_b32 s36, 0x50000
	s_mov_b32 s37, 0x60000
	s_mov_b32 s38, 0x70000
	s_movk_i32 s39, 0x90
	s_mov_b32 s40, 0x2957000
	s_mov_b32 s41, 0x2967000
	s_mov_b32 s42, 0x2977000
	s_mov_b32 s43, 0x2987000
	s_mov_b32 s44, 0x2997000
	s_mov_b32 s45, 0x29a7000
	s_mov_b32 s46, 0x29b7000
	s_mov_b32 s47, 0x29c7000
	s_movk_i32 s48, 0x80
	s_movk_i32 s49, 0x440
	s_movk_i32 s50, 0x7fff
	s_movk_i32 s51, 0x920
	s_mov_b64 s[10:11], 0x7157900
	s_movk_i32 s52, 0x110
	s_movk_i32 s53, 0x1240
	s_mov_b32 s54, 0
	s_branch .LBB0_295

.LBB0_311:
	s_cmp_lt_i32 s92, 4
	s_cselect_b64 s[16:17], -1, 0
	s_cmp_gt_i32 s92, 3
	s_cselect_b64 s[0:1], -1, 0
	s_cmp_lt_i32 s93, 4
	s_cselect_b64 s[2:3], -1, 0
	s_or_b64 s[0:1], s[0:1], s[2:3]
	s_and_b64 vcc, exec, s[0:1]
	s_cbranch_vccnz .LBB0_436
	s_andn2_b64 vcc, exec, s[6:7]
	s_cbranch_vccnz .LBB0_366
	s_waitcnt vmcnt(0)
	s_waitcnt lgkmcnt(0)
	s_setprio 0
	s_barrier
	s_and_saveexec_b64 s[0:1], s[64:65]
	s_cbranch_execz .LBB0_365
	v_mov_b32_e32 v0, 0
	s_waitcnt vmcnt(0) expcnt(0) lgkmcnt(0)
	ds_read_b32 v2, v0 offset:59392
	ds_read_b32 v1, v0 offset:59396
	s_waitcnt lgkmcnt(1)
	v_cmp_ne_u32_e32 vcc, 0, v2
	s_cbranch_vccnz .LBB0_329
	v_readlane_b32 s2, v254, 2
	s_mul_i32 s52, s95, s2
	s_add_u32 s2, s30, 0x2954500
	s_addc_u32 s3, s31, 0
	s_add_u32 s4, s30, 0x2954700
	s_addc_u32 s5, s31, 0
	s_add_u32 s6, s30, 0x2954800
	s_addc_u32 s7, s31, 0
	s_add_u32 s8, s30, 0x2954900
	s_addc_u32 s9, s31, 0
	s_add_u32 s10, s30, 0x2954a00
	s_addc_u32 s11, s31, 0
	s_add_u32 s12, s30, 0x2954b00
	s_addc_u32 s13, s31, 0
	s_add_u32 s18, s30, 0x2954c00
	s_addc_u32 s19, s31, 0
	s_add_u32 s20, s30, 0x2954d00
	s_addc_u32 s21, s31, 0
	s_add_u32 s22, s30, 0x2954e00
	s_addc_u32 s23, s31, 0
	s_add_u32 s24, s30, 0x2954f00
	s_addc_u32 s25, s31, 0
	s_add_u32 s26, s30, 0x2955000
	s_addc_u32 s27, s31, 0
	s_add_u32 s34, s30, 0x2955100
	s_addc_u32 s35, s31, 0
	s_add_u32 s36, s30, 0x2955200
	s_addc_u32 s37, s31, 0
	s_add_u32 s38, s30, 0x2955300
	s_addc_u32 s39, s31, 0
	s_add_u32 s40, s30, 0x2955400
	s_addc_u32 s41, s31, 0
	s_add_u32 s42, s30, 0x2955500
	s_addc_u32 s43, s31, 0
	s_add_u32 s44, s30, 0x2955600
	s_mul_i32 s52, s52, s94
	s_addc_u32 s45, s31, 0
	s_mov_b32 s53, 1
	s_branch .LBB0_317

.LBB0_823:
	s_or_b64 exec, exec, s[2:3]
	s_waitcnt lgkmcnt(0)
	s_barrier
	s_cmpk_lt_u32 s96, 0x100
	s_cbranch_scc1 .Lprio_skip_6
	s_setprio 1
.Lprio_skip_6:
.LBB0_824:
	s_add_u32 s22, s30, 0x4c0000
	s_addc_u32 s23, s31, 0
	s_cmpk_lt_u32 s96, 0x900
	s_cselect_b64 s[4:5], -1, 0
	s_lshr_b32 s24, s96, 3
	s_and_b32 s35, s96, 7
	s_lshr_b32 s2, s94, 1
	s_cmp_ge_u32 s96, s2
	s_cselect_b64 s[2:3], -1, 0
	v_cndmask_b32_e64 v0, 0, 1, s[2:3]
	s_lshr_b32 s26, s94, 3
	v_cmp_ne_u32_e64 s[2:3], 1, v0
	v_cndmask_b32_e64 v0, 0, 1, s[4:5]
	s_mul_i32 s25, s35, 36
	s_lshl_b32 s27, s24, 7
	s_lshl_b32 s34, s26, 7
	s_mulk_i32 s35, 0x1200
	s_mov_b32 s7, 0
	v_cmp_ne_u32_e64 s[4:5], 1, v0
	s_movk_i32 s36, 0x48
	v_mov_b32_e32 v201, 0
	s_mov_b32 s37, 0x10000
	s_mov_b32 s38, 0x20000
	s_mov_b32 s39, 0x30000
	s_movk_i32 s40, 0x90
	s_movk_i32 s41, 0x1000
	s_movk_i32 s42, 0x2000
	s_movk_i32 s43, 0x3000
	s_mov_b32 s44, 0x8000
	s_mov_b32 s45, 0x9000
	s_mov_b32 s46, 0xa000
	s_mov_b32 s47, 0xb000
	s_mov_b32 s48, 0x11000
	s_mov_b32 s49, 0x12000
	s_mov_b32 s50, 0x13000
	s_mov_b32 s51, 0x18000
	s_mov_b32 s52, 0x19000
	s_mov_b32 s53, 0x1a000
	s_mov_b32 s54, 0x1b000
	s_movk_i32 s55, 0x7fff
	s_mov_b32 s56, 0
	s_branch .LBB0_827

.LBB0_847:
	s_cmp_lt_i32 s92, 8
	s_cselect_b64 s[8:9], -1, 0
	s_cmp_gt_i32 s92, 7
	s_cselect_b64 s[2:3], -1, 0
	s_cmp_lt_i32 s93, 8
	s_cselect_b64 s[4:5], -1, 0
	s_or_b64 s[2:3], s[2:3], s[4:5]
	s_and_b64 vcc, exec, s[2:3]
	s_cbranch_vccnz .LBB0_929
	s_andn2_b64 vcc, exec, s[0:1]
	s_cbranch_vccnz .LBB0_902
	s_waitcnt vmcnt(0)
	s_waitcnt lgkmcnt(0)
	s_setprio 0
	s_barrier
	s_and_saveexec_b64 s[0:1], s[64:65]
	s_cbranch_execz .LBB0_901
	v_mov_b32_e32 v0, 0
	s_waitcnt vmcnt(0) expcnt(0) lgkmcnt(0)
	ds_read_b32 v2, v0 offset:59392
	ds_read_b32 v1, v0 offset:59396
	s_waitcnt lgkmcnt(1)
	v_cmp_ne_u32_e32 vcc, 0, v2
	s_cbranch_vccnz .LBB0_865
	v_readlane_b32 s2, v254, 2
	s_mul_i32 s52, s95, s2
	s_add_u32 s2, s30, 0x2954500
	s_addc_u32 s3, s31, 0
	s_add_u32 s4, s30, 0x2954700
	s_addc_u32 s5, s31, 0
	s_add_u32 s6, s30, 0x2954800
	s_addc_u32 s7, s31, 0
	s_add_u32 s10, s30, 0x2954900
	s_addc_u32 s11, s31, 0
	s_add_u32 s12, s30, 0x2954a00
	s_addc_u32 s13, s31, 0
	s_add_u32 s16, s30, 0x2954b00
	s_addc_u32 s17, s31, 0
	s_add_u32 s18, s30, 0x2954c00
	s_addc_u32 s19, s31, 0
	s_add_u32 s20, s30, 0x2954d00
	s_addc_u32 s21, s31, 0
	s_add_u32 s22, s30, 0x2954e00
	s_addc_u32 s23, s31, 0
	s_add_u32 s24, s30, 0x2954f00
	s_addc_u32 s25, s31, 0
	s_add_u32 s26, s30, 0x2955000
	s_addc_u32 s27, s31, 0
	s_add_u32 s34, s30, 0x2955100
	s_addc_u32 s35, s31, 0
	s_add_u32 s36, s30, 0x2955200
	s_addc_u32 s37, s31, 0
	s_add_u32 s38, s30, 0x2955300
	s_addc_u32 s39, s31, 0
	s_add_u32 s40, s30, 0x2955400
	s_addc_u32 s41, s31, 0
	s_add_u32 s42, s30, 0x2955500
	s_addc_u32 s43, s31, 0
	s_add_u32 s44, s30, 0x2955600
	s_mul_i32 s52, s52, s94
	s_addc_u32 s45, s31, 0
	s_mov_b32 s53, 1
	s_branch .LBB0_853

.Lprio_skip_5:
.LBB0_984:
	s_add_u32 s16, s30, 0x6c0000
	s_addc_u32 s17, s31, 0
	s_lshl_b32 s2, s96, 3
	s_and_b32 s18, s2, 24
	s_cmpk_lt_u32 s96, 0x1200
	s_cselect_b64 s[4:5], -1, 0
	s_bfe_i32 s2, s96, 0x10002
	s_lshr_b32 s19, s96, 3
	s_and_b32 s21, s2, 0x48
	s_lshr_b32 s2, s94, 1
	s_cmp_ge_u32 s96, s2
	s_cselect_b64 s[2:3], -1, 0
	v_cndmask_b32_e64 v0, 0, 1, s[2:3]
	s_and_b32 s6, s96, 3
	v_cmp_ne_u32_e64 s[2:3], 1, v0
	v_cndmask_b32_e64 v0, 0, 1, s[4:5]
	s_movk_i32 s20, 0x48
	s_lshr_b32 s22, s94, 3
	s_lshl_b32 s23, s6, 10
	s_mov_b32 s7, 0
	v_cmp_ne_u32_e64 s[4:5], 1, v0
	v_mov_b32_e32 v177, 0
	s_mov_b32 s24, 0x10000
	s_mov_b32 s25, 0x20000
	s_mov_b32 s26, 0x30000
	s_mov_b32 s27, 0x40000
	s_mov_b32 s34, 0x50000
	s_mov_b32 s35, 0x60000
	s_mov_b32 s36, 0x70000
	s_movk_i32 s37, 0x90
	s_mov_b32 s38, 0x2957000
	s_mov_b32 s39, 0x2967000
	s_mov_b32 s40, 0x2977000
	s_mov_b32 s41, 0x2987000
	s_mov_b32 s42, 0x2997000
	s_mov_b32 s43, 0x29a7000
	s_mov_b32 s44, 0x29b7000
	s_mov_b32 s45, 0x29c7000
	s_mov_b32 s46, 0x6c0000
	s_mov_b32 s47, 0x6d0000
	s_mov_b32 s48, 0x6e0000
	s_mov_b32 s49, 0x6f0000
	s_movk_i32 s50, 0x80
	s_movk_i32 s51, 0x440
	s_movk_i32 s52, 0x7fff
	s_mov_b64 s[8:9], 0x7157900
	s_movk_i32 s53, 0x110
	s_mov_b32 s54, 0
	s_branch .LBB0_987

.LBB0_1002:
	s_cmp_lt_i32 s92, 10
	s_cselect_b64 s[6:7], -1, 0
	s_cmp_gt_i32 s92, 9
	s_cselect_b64 s[2:3], -1, 0
	s_cmp_lt_i32 s93, 10
	s_cselect_b64 s[4:5], -1, 0
	s_or_b64 s[2:3], s[2:3], s[4:5]
	s_and_b64 vcc, exec, s[2:3]
	s_cbranch_vccnz .LBB0_1080
	s_andn2_b64 vcc, exec, s[0:1]
	s_cbranch_vccnz .LBB0_1057
	s_waitcnt vmcnt(0)
	s_waitcnt lgkmcnt(0)
	s_setprio 0
	s_barrier
	s_and_saveexec_b64 s[0:1], s[64:65]
	s_cbranch_execz .LBB0_1056
	v_mov_b32_e32 v0, 0
	s_waitcnt vmcnt(0) expcnt(0) lgkmcnt(0)
	ds_read_b32 v2, v0 offset:59392
	ds_read_b32 v1, v0 offset:59396
	s_waitcnt lgkmcnt(1)
	v_cmp_ne_u32_e32 vcc, 0, v2
	s_cbranch_vccnz .LBB0_1020
	v_readlane_b32 s2, v254, 2
	s_mul_i32 s52, s95, s2
	s_add_u32 s2, s30, 0x2954500
	s_addc_u32 s3, s31, 0
	s_add_u32 s4, s30, 0x2954700
	s_addc_u32 s5, s31, 0
	s_add_u32 s8, s30, 0x2954800
	s_addc_u32 s9, s31, 0
	s_add_u32 s10, s30, 0x2954900
	s_addc_u32 s11, s31, 0
	s_add_u32 s12, s30, 0x2954a00
	s_addc_u32 s13, s31, 0
	s_add_u32 s16, s30, 0x2954b00
	s_addc_u32 s17, s31, 0
	s_add_u32 s18, s30, 0x2954c00
	s_addc_u32 s19, s31, 0
	s_add_u32 s20, s30, 0x2954d00
	s_addc_u32 s21, s31, 0
	s_add_u32 s22, s30, 0x2954e00
	s_addc_u32 s23, s31, 0
	s_add_u32 s24, s30, 0x2954f00
	s_addc_u32 s25, s31, 0
	s_add_u32 s26, s30, 0x2955000
	s_addc_u32 s27, s31, 0
	s_add_u32 s34, s30, 0x2955100
	s_addc_u32 s35, s31, 0
	s_add_u32 s36, s30, 0x2955200
	s_addc_u32 s37, s31, 0
	s_add_u32 s38, s30, 0x2955300
	s_addc_u32 s39, s31, 0
	s_add_u32 s40, s30, 0x2955400
	s_addc_u32 s41, s31, 0
	s_add_u32 s42, s30, 0x2955500
	s_addc_u32 s43, s31, 0
	s_add_u32 s44, s30, 0x2955600
	s_mul_i32 s52, s52, s94
	s_addc_u32 s45, s31, 0
	s_mov_b32 s53, 1
	s_branch .LBB0_1008

.Lprio_skip_4:
.LBB0_1057:
	s_add_u32 s22, s30, 0xec0000
	s_addc_u32 s23, s31, 0
	s_cmpk_lt_u32 s96, 0x900
	s_cselect_b64 s[4:5], -1, 0
	s_lshr_b32 s24, s96, 3
	s_and_b32 s37, s96, 7
	s_add_u32 s26, s30, 0x7157900
	s_addc_u32 s27, s31, 0
	s_lshr_b32 s0, s94, 1
	s_cmp_ge_u32 s96, s0
	s_cselect_b64 s[2:3], -1, 0
	v_cndmask_b32_e64 v0, 0, 1, s[2:3]
	s_lshr_b32 s34, s94, 3
	v_cmp_ne_u32_e64 s[2:3], 1, v0
	v_cndmask_b32_e64 v0, 0, 1, s[4:5]
	s_mul_i32 s25, s37, 36
	s_lshl_b32 s35, s24, 7
	s_lshl_b32 s36, s34, 7
	s_mulk_i32 s37, 0x1200
	s_mov_b32 s1, 0
	v_cmp_ne_u32_e64 s[4:5], 1, v0
	s_movk_i32 s38, 0x48
	v_mov_b32_e32 v201, 0
	s_mov_b32 s39, 0x40000
	s_mov_b32 s40, 0x80000
	s_mov_b32 s41, 0xc0000
	s_movk_i32 s42, 0x90
	s_movk_i32 s43, 0x1000
	s_movk_i32 s44, 0x2000
	s_movk_i32 s45, 0x3000
	s_mov_b32 s46, 0x8000
	s_mov_b32 s47, 0x9000
	s_mov_b32 s48, 0xa000
	s_mov_b32 s49, 0xb000
	s_mov_b32 s50, 0x10000
	s_mov_b32 s51, 0x11000
	s_mov_b32 s52, 0x12000
	s_mov_b32 s53, 0x13000
	s_mov_b32 s54, 0x18000
	s_mov_b32 s55, 0x19000
	s_mov_b32 s56, 0x1a000
	s_mov_b32 s57, 0x1b000
	s_movk_i32 s58, 0x7fff
	s_mov_b32 s59, 0
	s_branch .LBB0_1060

.LBB0_1080:
	s_cmp_lt_i32 s92, 11
	s_cselect_b64 s[54:55], -1, 0
	s_cmp_gt_i32 s92, 10
	s_cselect_b64 s[0:1], -1, 0
	s_cmp_lt_i32 s93, 11
	s_cselect_b64 s[2:3], -1, 0
	s_or_b64 s[0:1], s[0:1], s[2:3]
	s_and_b64 vcc, exec, s[0:1]
	s_cbranch_vccnz .LBB0_1217
	s_andn2_b64 vcc, exec, s[6:7]
	s_cbranch_vccnz .LBB0_1135
	s_waitcnt vmcnt(0)
	s_waitcnt lgkmcnt(0)
	s_setprio 0
	s_barrier
	s_and_saveexec_b64 s[0:1], s[64:65]
	s_cbranch_execz .LBB0_1134
	v_mov_b32_e32 v0, 0
	s_waitcnt vmcnt(0) expcnt(0) lgkmcnt(0)
	ds_read_b32 v2, v0 offset:59392
	ds_read_b32 v1, v0 offset:59396
	s_waitcnt lgkmcnt(1)
	v_cmp_ne_u32_e32 vcc, 0, v2
	s_cbranch_vccnz .LBB0_1098
	v_readlane_b32 s2, v254, 2
	s_mul_i32 s52, s95, s2
	s_add_u32 s2, s30, 0x2954500
	s_addc_u32 s3, s31, 0
	s_add_u32 s4, s30, 0x2954700
	s_addc_u32 s5, s31, 0
	s_add_u32 s6, s30, 0x2954800
	s_addc_u32 s7, s31, 0
	s_add_u32 s10, s30, 0x2954900
	s_addc_u32 s11, s31, 0
	s_add_u32 s12, s30, 0x2954a00
	s_addc_u32 s13, s31, 0
	s_add_u32 s16, s30, 0x2954b00
	s_addc_u32 s17, s31, 0
	s_add_u32 s18, s30, 0x2954c00
	s_addc_u32 s19, s31, 0
	s_add_u32 s20, s30, 0x2954d00
	s_addc_u32 s21, s31, 0
	s_add_u32 s22, s30, 0x2954e00
	s_addc_u32 s23, s31, 0
	s_add_u32 s24, s30, 0x2954f00
	s_addc_u32 s25, s31, 0
	s_add_u32 s26, s30, 0x2955000
	s_addc_u32 s27, s31, 0
	s_add_u32 s34, s30, 0x2955100
	s_addc_u32 s35, s31, 0
	s_add_u32 s36, s30, 0x2955200
	s_addc_u32 s37, s31, 0
	s_add_u32 s38, s30, 0x2955300
	s_addc_u32 s39, s31, 0
	s_add_u32 s40, s30, 0x2955400
	s_addc_u32 s41, s31, 0
	s_add_u32 s42, s30, 0x2955500
	s_addc_u32 s43, s31, 0
	s_add_u32 s44, s30, 0x2955600
	s_mul_i32 s52, s52, s94
	s_addc_u32 s45, s31, 0
	s_mov_b32 s53, 1
	s_branch .LBB0_1086

.Lprio_skip_3:
.LBB0_1272:
	s_and_b32 s19, s96, 3
	s_mul_i32 s19, s19, 5
	v_sub_u32_e64 v0, s19, 14 clamp
	s_lshr_b32 s18, s96, 3
	v_readfirstlane_b32 s0, v0
	s_xor_b32 s20, s0, 5
	v_cvt_f32_ubyte0_e32 v0, s20
	v_rcp_iflag_f32_e32 v0, v0
	s_mul_i32 s22, s20, 0x48
	s_cmp_lt_u32 s18, s22
	s_cselect_b64 s[0:1], -1, 0
	v_mul_f32_e32 v0, 0x4f7ffffe, v0
	v_cvt_u32_f32_e32 v0, v0
	s_bfe_i32 s2, s96, 0x10002
	s_and_b32 s23, s2, 0x48
	s_lshr_b32 s2, s94, 1
	s_cmp_ge_u32 s96, s2
	s_cselect_b64 s[2:3], -1, 0
	s_sub_i32 s4, 0, s20
	v_readfirstlane_b32 s5, v0
	s_mul_i32 s4, s4, s5
	v_cndmask_b32_e64 v0, 0, 1, s[2:3]
	s_mul_hi_u32 s4, s5, s4
	v_cmp_ne_u32_e64 s[2:3], 1, v0
	v_cndmask_b32_e64 v0, 0, 1, s[0:1]
	s_movk_i32 s21, 0x48
	s_lshr_b32 s24, s94, 3
	s_mov_b32 s9, 0
	s_add_i32 s25, s5, s4
	v_cmp_ne_u32_e64 s[4:5], 1, v0
	s_mov_b32 s26, 0x1c71c8
	v_mov_b32_e32 v177, 0
	s_mov_b32 s27, 0x10000
	s_mov_b32 s34, 0x20000
	s_mov_b32 s35, 0x30000
	s_mov_b32 s36, 0x40000
	s_mov_b32 s37, 0x50000
	s_mov_b32 s38, 0x60000
	s_mov_b32 s39, 0x70000
	s_movk_i32 s40, 0x90
	s_mov_b32 s41, 0x2957000
	s_mov_b32 s42, 0x2967000
	s_mov_b32 s43, 0x2977000
	s_mov_b32 s44, 0x2987000
	s_mov_b32 s45, 0x2997000
	s_mov_b32 s46, 0x29a7000
	s_mov_b32 s47, 0x29b7000
	s_mov_b32 s48, 0x29c7000
	s_movk_i32 s49, 0x80
	s_movk_i32 s50, 0x440
	s_movk_i32 s51, 0x7fff
	s_movk_i32 s52, 0x920
	s_mov_b64 s[10:11], 0x7157900
	s_movk_i32 s53, 0x110
	s_movk_i32 s54, 0x1240
	s_mov_b32 s55, 0
	s_branch .LBB0_1275

.LBB0_1293:
	s_cmp_lt_i32 s92, 13
	s_cselect_b64 s[16:17], -1, 0
	s_cmp_gt_i32 s92, 12
	s_cselect_b64 s[0:1], -1, 0
	s_cmp_lt_i32 s93, 13
	s_cselect_b64 s[2:3], -1, 0
	s_or_b64 s[0:1], s[0:1], s[2:3]
	s_and_b64 vcc, exec, s[0:1]
	s_cbranch_vccnz .LBB0_1419
	s_andn2_b64 vcc, exec, s[6:7]
	s_cbranch_vccnz .LBB0_1348
	s_waitcnt vmcnt(0)
	s_waitcnt lgkmcnt(0)
	s_setprio 0
	s_barrier
	s_and_saveexec_b64 s[0:1], s[64:65]
	s_cbranch_execz .LBB0_1347
	v_mov_b32_e32 v0, 0
	s_waitcnt vmcnt(0) expcnt(0) lgkmcnt(0)
	ds_read_b32 v2, v0 offset:59392
	ds_read_b32 v1, v0 offset:59396
	s_waitcnt lgkmcnt(1)
	v_cmp_ne_u32_e32 vcc, 0, v2
	s_cbranch_vccnz .LBB0_1311
	v_readlane_b32 s2, v254, 2
	s_mul_i32 s52, s95, s2
	s_add_u32 s2, s30, 0x2954500
	s_addc_u32 s3, s31, 0
	s_add_u32 s4, s30, 0x2954700
	s_addc_u32 s5, s31, 0
	s_add_u32 s6, s30, 0x2954800
	s_addc_u32 s7, s31, 0
	s_add_u32 s8, s30, 0x2954900
	s_addc_u32 s9, s31, 0
	s_add_u32 s10, s30, 0x2954a00
	s_addc_u32 s11, s31, 0
	s_add_u32 s12, s30, 0x2954b00
	s_addc_u32 s13, s31, 0
	s_add_u32 s18, s30, 0x2954c00
	s_addc_u32 s19, s31, 0
	s_add_u32 s20, s30, 0x2954d00
	s_addc_u32 s21, s31, 0
	s_add_u32 s22, s30, 0x2954e00
	s_addc_u32 s23, s31, 0
	s_add_u32 s24, s30, 0x2954f00
	s_addc_u32 s25, s31, 0
	s_add_u32 s26, s30, 0x2955000
	s_addc_u32 s27, s31, 0
	s_add_u32 s34, s30, 0x2955100
	s_addc_u32 s35, s31, 0
	s_add_u32 s36, s30, 0x2955200
	s_addc_u32 s37, s31, 0
	s_add_u32 s38, s30, 0x2955300
	s_addc_u32 s39, s31, 0
	s_add_u32 s40, s30, 0x2955400
	s_addc_u32 s41, s31, 0
	s_add_u32 s42, s30, 0x2955500
	s_addc_u32 s43, s31, 0
	s_add_u32 s44, s30, 0x2955600
	s_mul_i32 s52, s52, s94
	s_addc_u32 s45, s31, 0
	s_mov_b32 s53, 1
	s_branch .LBB0_1299

.Lprio_skip_2:
.LBB0_1804:
	s_add_u32 s22, s30, 0x4c0000
	s_addc_u32 s23, s31, 0
	s_cmpk_lt_u32 s96, 0x800
	s_cselect_b64 s[4:5], -1, 0
	s_lshl_b32 s2, s96, 5
	s_lshr_b32 s24, s96, 3
	s_and_b32 s25, s2, 0xe0
	s_lshr_b32 s2, s94, 1
	s_cmp_ge_u32 s96, s2
	s_cselect_b64 s[2:3], -1, 0
	v_cndmask_b32_e64 v0, 0, 1, s[2:3]
	s_lshr_b32 s26, s94, 3
	v_cmp_ne_u32_e64 s[2:3], 1, v0
	v_cndmask_b32_e64 v0, 0, 1, s[4:5]
	s_lshl_b32 s27, s24, 7
	s_lshl_b32 s34, s26, 7
	s_mov_b32 s7, 0
	v_cmp_ne_u32_e64 s[4:5], 1, v0
	s_movk_i32 s35, 0x48
	v_mov_b32_e32 v201, 0
	s_mov_b32 s36, 0x10000
	s_mov_b32 s37, 0x20000
	s_mov_b32 s38, 0x30000
	s_movk_i32 s39, 0x90
	s_movk_i32 s40, 0x1000
	s_movk_i32 s41, 0x2000
	s_movk_i32 s42, 0x3000
	s_mov_b32 s43, 0x8000
	s_mov_b32 s44, 0x9000
	s_mov_b32 s45, 0xa000
	s_mov_b32 s46, 0xb000
	s_mov_b32 s47, 0x11000
	s_mov_b32 s48, 0x12000
	s_mov_b32 s49, 0x13000
	s_mov_b32 s50, 0x18000
	s_mov_b32 s51, 0x19000
	s_mov_b32 s52, 0x1a000
	s_mov_b32 s53, 0x1b000
	s_movk_i32 s54, 0x7fff
	s_mov_b32 s55, 0
	s_branch .LBB0_1807

.LBB0_1827:
	s_cmp_lt_i32 s92, 17
	s_cselect_b64 s[8:9], -1, 0
	s_cmp_gt_i32 s92, 16
	s_cselect_b64 s[2:3], -1, 0
	s_cmp_lt_i32 s93, 17
	s_cselect_b64 s[4:5], -1, 0
	s_or_b64 s[2:3], s[2:3], s[4:5]
	s_and_b64 vcc, exec, s[2:3]
	s_cbranch_vccnz .LBB0_1909
	s_andn2_b64 vcc, exec, s[0:1]
	s_cbranch_vccnz .LBB0_1882
	s_waitcnt vmcnt(0)
	s_waitcnt lgkmcnt(0)
	s_setprio 0
	s_barrier
	s_and_saveexec_b64 s[0:1], s[64:65]
	s_cbranch_execz .LBB0_1881
	v_mov_b32_e32 v0, 0
	s_waitcnt vmcnt(0) expcnt(0) lgkmcnt(0)
	ds_read_b32 v2, v0 offset:59392
	ds_read_b32 v1, v0 offset:59396
	s_waitcnt lgkmcnt(1)
	v_cmp_ne_u32_e32 vcc, 0, v2
	s_cbranch_vccnz .LBB0_1845
	v_readlane_b32 s2, v254, 2
	s_mul_i32 s52, s95, s2
	s_add_u32 s2, s30, 0x2954500
	s_addc_u32 s3, s31, 0
	s_add_u32 s4, s30, 0x2954700
	s_addc_u32 s5, s31, 0
	s_add_u32 s6, s30, 0x2954800
	s_addc_u32 s7, s31, 0
	s_add_u32 s10, s30, 0x2954900
	s_addc_u32 s11, s31, 0
	s_add_u32 s12, s30, 0x2954a00
	s_addc_u32 s13, s31, 0
	s_add_u32 s16, s30, 0x2954b00
	s_addc_u32 s17, s31, 0
	s_add_u32 s18, s30, 0x2954c00
	s_addc_u32 s19, s31, 0
	s_add_u32 s20, s30, 0x2954d00
	s_addc_u32 s21, s31, 0
	s_add_u32 s22, s30, 0x2954e00
	s_addc_u32 s23, s31, 0
	s_add_u32 s24, s30, 0x2954f00
	s_addc_u32 s25, s31, 0
	s_add_u32 s26, s30, 0x2955000
	s_addc_u32 s27, s31, 0
	s_add_u32 s34, s30, 0x2955100
	s_addc_u32 s35, s31, 0
	s_add_u32 s36, s30, 0x2955200
	s_addc_u32 s37, s31, 0
	s_add_u32 s38, s30, 0x2955300
	s_addc_u32 s39, s31, 0
	s_add_u32 s40, s30, 0x2955400
	s_addc_u32 s41, s31, 0
	s_add_u32 s42, s30, 0x2955500
	s_addc_u32 s43, s31, 0
	s_add_u32 s44, s30, 0x2955600
	s_mul_i32 s52, s52, s94
	s_addc_u32 s45, s31, 0
	s_mov_b32 s53, 1
	s_branch .LBB0_1833

.Lprio_skip_1:
.LBB0_1964:
	s_add_u32 s16, s30, 0x6c0000
	s_addc_u32 s17, s31, 0
	s_lshl_b32 s2, s96, 3
	s_and_b32 s18, s2, 24
	s_cmpk_lt_u32 s96, 0x1000
	s_cselect_b64 s[4:5], -1, 0
	s_lshl_b32 s2, s96, 4
	s_lshr_b32 s19, s96, 3
	s_and_b32 s20, s2, 64
	s_lshr_b32 s2, s94, 1
	s_cmp_ge_u32 s96, s2
	s_cselect_b64 s[2:3], -1, 0
	v_cndmask_b32_e64 v0, 0, 1, s[2:3]
	s_and_b32 s6, s96, 3
	v_cmp_ne_u32_e64 s[2:3], 1, v0
	v_cndmask_b32_e64 v0, 0, 1, s[4:5]
	s_lshr_b32 s21, s94, 3
	s_lshl_b32 s22, s6, 10
	s_mov_b32 s7, 0
	v_cmp_ne_u32_e64 s[4:5], 1, v0
	v_mov_b32_e32 v177, 0
	s_movk_i32 s23, 0x48
	s_mov_b32 s24, 0x10000
	s_mov_b32 s25, 0x20000
	s_mov_b32 s26, 0x30000
	s_mov_b32 s27, 0x40000
	s_mov_b32 s34, 0x50000
	s_mov_b32 s35, 0x60000
	s_mov_b32 s36, 0x70000
	s_movk_i32 s37, 0x90
	s_mov_b32 s38, 0x2957000
	s_mov_b32 s39, 0x2967000
	s_mov_b32 s40, 0x2977000
	s_mov_b32 s41, 0x2987000
	s_mov_b32 s42, 0x2997000
	s_mov_b32 s43, 0x29a7000
	s_mov_b32 s44, 0x29b7000
	s_mov_b32 s45, 0x29c7000
	s_mov_b32 s46, 0x6c0000
	s_mov_b32 s47, 0x6d0000
	s_mov_b32 s48, 0x6e0000
	s_mov_b32 s49, 0x6f0000
	s_movk_i32 s50, 0x80
	s_movk_i32 s51, 0x440
	s_movk_i32 s52, 0x7fff
	s_mov_b64 s[8:9], 0x7157900
	s_movk_i32 s53, 0x110
	s_mov_b32 s54, 0
	s_branch .LBB0_1967

.LBB0_1982:
	s_cmp_lt_i32 s92, 19
	s_cselect_b64 s[6:7], -1, 0
	s_cmp_gt_i32 s92, 18
	s_cselect_b64 s[2:3], -1, 0
	s_cmp_lt_i32 s93, 19
	s_cselect_b64 s[4:5], -1, 0
	s_or_b64 s[2:3], s[2:3], s[4:5]
	s_and_b64 vcc, exec, s[2:3]
	s_cbranch_vccnz .LBB0_2060
	s_andn2_b64 vcc, exec, s[0:1]
	s_cbranch_vccnz .LBB0_2037
	s_waitcnt vmcnt(0)
	s_waitcnt lgkmcnt(0)
	s_setprio 0
	s_barrier
	s_and_saveexec_b64 s[0:1], s[64:65]
	s_cbranch_execz .LBB0_2036
	v_mov_b32_e32 v0, 0
	s_waitcnt vmcnt(0) expcnt(0) lgkmcnt(0)
	ds_read_b32 v2, v0 offset:59392
	ds_read_b32 v1, v0 offset:59396
	s_waitcnt lgkmcnt(1)
	v_cmp_ne_u32_e32 vcc, 0, v2
	s_cbranch_vccnz .LBB0_2000
	v_readlane_b32 s2, v254, 2
	s_mul_i32 s50, s95, s2
	s_add_u32 s2, s30, 0x2954500
	s_addc_u32 s3, s31, 0
	s_add_u32 s4, s30, 0x2954700
	s_addc_u32 s5, s31, 0
	s_add_u32 s8, s30, 0x2954800
	s_addc_u32 s9, s31, 0
	s_add_u32 s10, s30, 0x2954900
	s_addc_u32 s11, s31, 0
	s_add_u32 s12, s30, 0x2954a00
	s_addc_u32 s13, s31, 0
	s_add_u32 s14, s30, 0x2954b00
	s_addc_u32 s15, s31, 0
	s_add_u32 s16, s30, 0x2954c00
	s_addc_u32 s17, s31, 0
	s_add_u32 s18, s30, 0x2954d00
	s_addc_u32 s19, s31, 0
	s_add_u32 s20, s30, 0x2954e00
	s_addc_u32 s21, s31, 0
	s_add_u32 s22, s30, 0x2954f00
	s_addc_u32 s23, s31, 0
	s_add_u32 s24, s30, 0x2955000
	s_addc_u32 s25, s31, 0
	s_add_u32 s26, s30, 0x2955100
	s_addc_u32 s27, s31, 0
	s_add_u32 s34, s30, 0x2955200
	s_addc_u32 s35, s31, 0
	s_add_u32 s36, s30, 0x2955300
	s_addc_u32 s37, s31, 0
	s_add_u32 s38, s30, 0x2955400
	s_addc_u32 s39, s31, 0
	s_add_u32 s40, s30, 0x2955500
	s_addc_u32 s41, s31, 0
	s_add_u32 s42, s30, 0x2955600
	s_mul_i32 s50, s50, s94
	s_addc_u32 s43, s31, 0
	s_mov_b32 s51, 1
	s_branch .LBB0_1988

.Lprio_skip_0:
.LBB0_2037:
	s_add_u32 s20, s30, 0xec0000
	s_addc_u32 s21, s31, 0
	s_cmpk_lt_u32 s96, 0x800
	s_cselect_b64 s[4:5], -1, 0
	s_lshl_b32 s0, s96, 5
	s_lshr_b32 s22, s96, 3
	s_and_b32 s23, s0, 0xe0
	s_add_u32 s24, s30, 0x7157900
	s_addc_u32 s25, s31, 0
	s_lshr_b32 s0, s94, 1
	s_cmp_ge_u32 s96, s0
	s_cselect_b64 s[2:3], -1, 0
	v_cndmask_b32_e64 v0, 0, 1, s[2:3]
	s_lshr_b32 s26, s94, 3
	v_cmp_ne_u32_e64 s[2:3], 1, v0
	v_cndmask_b32_e64 v0, 0, 1, s[4:5]
	s_lshl_b32 s27, s22, 7
	s_lshl_b32 s34, s26, 7
	s_mov_b32 s1, 0
	v_cmp_ne_u32_e64 s[4:5], 1, v0
	s_movk_i32 s35, 0x48
	v_mov_b32_e32 v201, 0
	s_mov_b32 s36, 0x40000
	s_mov_b32 s37, 0x80000
	s_mov_b32 s38, 0xc0000
	s_movk_i32 s39, 0x90
	s_movk_i32 s40, 0x1000
	s_movk_i32 s41, 0x2000
	s_movk_i32 s42, 0x3000
	s_mov_b32 s43, 0x8000
	s_mov_b32 s44, 0x9000
	s_mov_b32 s45, 0xa000
	s_mov_b32 s46, 0xb000
	s_mov_b32 s47, 0x10000
	s_mov_b32 s48, 0x11000
	s_mov_b32 s49, 0x12000
	s_mov_b32 s50, 0x13000
	s_mov_b32 s51, 0x18000
	s_mov_b32 s52, 0x19000
	s_mov_b32 s53, 0x1a000
	s_mov_b32 s54, 0x1b000
	s_movk_i32 s55, 0x7fff
	s_mov_b32 s56, 0
	s_branch .LBB0_2040

.LBB0_2060:
	s_cmp_gt_i32 s92, 19
	s_cselect_b64 s[0:1], -1, 0
	s_cmp_lt_i32 s93, 20
	s_cselect_b64 s[2:3], -1, 0
	s_or_b64 s[0:1], s[0:1], s[2:3]
	s_and_b64 vcc, exec, s[0:1]
	s_cbranch_vccnz .LBB0_2126
	s_andn2_b64 vcc, exec, s[6:7]
	s_cbranch_vccnz .LBB0_2115
	s_waitcnt vmcnt(0)
	s_waitcnt lgkmcnt(0)
	s_setprio 0
	s_barrier
	s_and_saveexec_b64 s[0:1], s[64:65]
	s_cbranch_execz .LBB0_2114
	v_mov_b32_e32 v0, 0
	s_waitcnt vmcnt(0) expcnt(0) lgkmcnt(0)
	ds_read_b32 v2, v0 offset:59392
	ds_read_b32 v1, v0 offset:59396
	s_waitcnt lgkmcnt(1)
	v_cmp_ne_u32_e32 vcc, 0, v2
	s_cbranch_vccnz .LBB0_2078
	v_readlane_b32 s2, v254, 2
	s_mul_i32 s48, s95, s2
	s_add_u32 s2, s30, 0x2954500
	s_addc_u32 s3, s31, 0
	s_add_u32 s4, s30, 0x2954700
	s_addc_u32 s5, s31, 0
	s_add_u32 s6, s30, 0x2954800
	s_addc_u32 s7, s31, 0
	s_add_u32 s8, s30, 0x2954900
	s_addc_u32 s9, s31, 0
	s_add_u32 s10, s30, 0x2954a00
	s_addc_u32 s11, s31, 0
	s_add_u32 s12, s30, 0x2954b00
	s_addc_u32 s13, s31, 0
	s_add_u32 s14, s30, 0x2954c00
	s_addc_u32 s15, s31, 0
	s_add_u32 s16, s30, 0x2954d00
	s_addc_u32 s17, s31, 0
	s_add_u32 s18, s30, 0x2954e00
	s_addc_u32 s19, s31, 0
	s_add_u32 s20, s30, 0x2954f00
	s_addc_u32 s21, s31, 0
	s_add_u32 s22, s30, 0x2955000
	s_addc_u32 s23, s31, 0
	s_add_u32 s24, s30, 0x2955100
	s_addc_u32 s25, s31, 0
	s_add_u32 s26, s30, 0x2955200
	s_addc_u32 s27, s31, 0
	s_add_u32 s34, s30, 0x2955300
	s_addc_u32 s35, s31, 0
	s_add_u32 s36, s30, 0x2955400
	s_addc_u32 s37, s31, 0
	s_add_u32 s38, s30, 0x2955500
	s_addc_u32 s39, s31, 0
	s_add_u32 s40, s30, 0x2955600
	s_mul_i32 s48, s48, s94
	s_addc_u32 s41, s31, 0
	s_mov_b32 s49, 1
	s_branch .LBB0_2066
